# attention unit epilogue: 16 dwordx2 row-per-lane stores widened to 8 dwordx4 via v_permlane32_swap pairs (upper half-wave address +8)
# speedup vs baseline: 1.0028x; 1.0028x over previous
.LBB0_380:
	s_setprio 0
	v_mov_b32_e32 v0, v238
	s_nop 1
	v_permlane32_swap_b32_e32 v238, v0
	v_add_f32_e32 v0, v238, v0
	v_div_scale_f32 v2, s[0:1], v0, v0, 1.0
	v_rcp_f32_e32 v3, v2
	s_mov_b64 s[76:77], 0
	v_fma_f32 v4, -v2, v3, 1.0
	v_fmac_f32_e32 v3, v4, v3
	v_div_scale_f32 v4, vcc, 1.0, v0, 1.0
	v_mul_f32_e32 v5, v4, v3
	v_fma_f32 v6, -v2, v5, v4
	v_fmac_f32_e32 v5, v6, v3
	v_fma_f32 v2, -v2, v5, v4
	v_div_fmas_f32 v2, v2, v3, v5
	v_div_fixup_f32 v6, v2, v0, 1.0
	v_lshlrev_b64 v[2:3], 12, v[196:197]
	v_lshl_add_u64 v[2:3], s[58:59], 0, v[2:3]
	v_lshlrev_b32_e32 v0, 1, v234
	v_lshl_add_u64 v[2:3], v[2:3], 0, v[0:1]
	v_lshlrev_b32_e32 v12, 1, v234
	v_mov_b32_e32 v13, 0
	v_lshl_add_u64 v[2:3], v[2:3], 0, v[12:13]
	v_mul_f32_e32 v0, v80, v6
	v_mul_f32_e32 v4, v81, v6
	v_mul_f32_e32 v5, v83, v6
	v_cvt_pk_bf16_f32 v8, v0, v4
	v_mul_f32_e32 v0, v82, v6
	v_cvt_pk_bf16_f32 v9, v0, v5
	v_mul_f32_e32 v0, v84, v6
	v_mul_f32_e32 v4, v85, v6
	v_mul_f32_e32 v5, v87, v6
	v_cvt_pk_bf16_f32 v10, v0, v4
	v_mul_f32_e32 v0, v86, v6
	v_cvt_pk_bf16_f32 v11, v0, v5
	s_nop 1
	v_permlane32_swap_b32_e32 v8, v10
	v_permlane32_swap_b32_e32 v9, v11
	global_store_dwordx4 v[2:3], v[8:11], off
	v_mul_f32_e32 v0, v88, v6
	v_mul_f32_e32 v4, v89, v6
	v_mul_f32_e32 v5, v91, v6
	v_cvt_pk_bf16_f32 v8, v0, v4
	v_mul_f32_e32 v0, v90, v6
	v_cvt_pk_bf16_f32 v9, v0, v5
	v_mul_f32_e32 v0, v92, v6
	v_mul_f32_e32 v4, v93, v6
	v_mul_f32_e32 v5, v95, v6
	v_cvt_pk_bf16_f32 v10, v0, v4
	v_mul_f32_e32 v0, v94, v6
	v_cvt_pk_bf16_f32 v11, v0, v5
	s_nop 1
	v_permlane32_swap_b32_e32 v8, v10
	v_permlane32_swap_b32_e32 v9, v11
	global_store_dwordx4 v[2:3], v[8:11], off offset:32
	v_mul_f32_e32 v0, v64, v6
	v_mul_f32_e32 v4, v65, v6
	v_mul_f32_e32 v5, v67, v6
	v_cvt_pk_bf16_f32 v8, v0, v4
	v_mul_f32_e32 v0, v66, v6
	v_cvt_pk_bf16_f32 v9, v0, v5
	v_mul_f32_e32 v0, v68, v6
	v_mul_f32_e32 v4, v69, v6
	v_mul_f32_e32 v5, v71, v6
	v_cvt_pk_bf16_f32 v10, v0, v4
	v_mul_f32_e32 v0, v70, v6
	v_cvt_pk_bf16_f32 v11, v0, v5
	s_nop 1
	v_permlane32_swap_b32_e32 v8, v10
	v_permlane32_swap_b32_e32 v9, v11
	global_store_dwordx4 v[2:3], v[8:11], off offset:64
	v_mul_f32_e32 v0, v72, v6
	v_mul_f32_e32 v4, v73, v6
	v_mul_f32_e32 v5, v75, v6
	v_cvt_pk_bf16_f32 v8, v0, v4
	v_mul_f32_e32 v0, v74, v6
	v_cvt_pk_bf16_f32 v9, v0, v5
	v_mul_f32_e32 v0, v76, v6
	v_mul_f32_e32 v4, v77, v6
	v_mul_f32_e32 v5, v79, v6
	v_cvt_pk_bf16_f32 v10, v0, v4
	v_mul_f32_e32 v0, v78, v6
	v_cvt_pk_bf16_f32 v11, v0, v5
	s_nop 1
	v_permlane32_swap_b32_e32 v8, v10
	v_permlane32_swap_b32_e32 v9, v11
	global_store_dwordx4 v[2:3], v[8:11], off offset:96
	v_mul_f32_e32 v0, v48, v6
	v_mul_f32_e32 v4, v49, v6
	v_mul_f32_e32 v5, v51, v6
	v_cvt_pk_bf16_f32 v8, v0, v4
	v_mul_f32_e32 v0, v50, v6
	v_cvt_pk_bf16_f32 v9, v0, v5
	v_mul_f32_e32 v0, v52, v6
	v_mul_f32_e32 v4, v53, v6
	v_mul_f32_e32 v5, v55, v6
	v_cvt_pk_bf16_f32 v10, v0, v4
	v_mul_f32_e32 v0, v54, v6
	v_cvt_pk_bf16_f32 v11, v0, v5
	s_nop 1
	v_permlane32_swap_b32_e32 v8, v10
	v_permlane32_swap_b32_e32 v9, v11
	global_store_dwordx4 v[2:3], v[8:11], off offset:128
	v_mul_f32_e32 v0, v56, v6
	v_mul_f32_e32 v4, v57, v6
	v_mul_f32_e32 v5, v59, v6
	v_cvt_pk_bf16_f32 v8, v0, v4
	v_mul_f32_e32 v0, v58, v6
	v_cvt_pk_bf16_f32 v9, v0, v5
	v_mul_f32_e32 v0, v60, v6
	v_mul_f32_e32 v4, v61, v6
	v_mul_f32_e32 v5, v63, v6
	v_cvt_pk_bf16_f32 v10, v0, v4
	v_mul_f32_e32 v0, v62, v6
	v_cvt_pk_bf16_f32 v11, v0, v5
	s_nop 1
	v_permlane32_swap_b32_e32 v8, v10
	v_permlane32_swap_b32_e32 v9, v11
	global_store_dwordx4 v[2:3], v[8:11], off offset:160
	v_mul_f32_e32 v0, v32, v6
	v_mul_f32_e32 v4, v33, v6
	v_mul_f32_e32 v5, v35, v6
	v_cvt_pk_bf16_f32 v8, v0, v4
	v_mul_f32_e32 v0, v34, v6
	v_cvt_pk_bf16_f32 v9, v0, v5
	v_mul_f32_e32 v0, v36, v6
	v_mul_f32_e32 v4, v37, v6
	v_mul_f32_e32 v5, v39, v6
	v_cvt_pk_bf16_f32 v10, v0, v4
	v_mul_f32_e32 v0, v38, v6
	v_cvt_pk_bf16_f32 v11, v0, v5
	s_nop 1
	v_permlane32_swap_b32_e32 v8, v10
	v_permlane32_swap_b32_e32 v9, v11
	global_store_dwordx4 v[2:3], v[8:11], off offset:192
	v_mul_f32_e32 v0, v40, v6
	v_mul_f32_e32 v4, v41, v6
	v_mul_f32_e32 v5, v43, v6
	v_cvt_pk_bf16_f32 v8, v0, v4
	v_mul_f32_e32 v0, v42, v6
	v_cvt_pk_bf16_f32 v9, v0, v5
	v_mul_f32_e32 v0, v44, v6
	v_mul_f32_e32 v4, v45, v6
	v_mul_f32_e32 v5, v47, v6
	s_and_b64 vcc, exec, s[78:79]
	v_cvt_pk_bf16_f32 v10, v0, v4
	v_mul_f32_e32 v0, v46, v6
	v_cvt_pk_bf16_f32 v11, v0, v5
	s_nop 1
	v_permlane32_swap_b32_e32 v8, v10
	v_permlane32_swap_b32_e32 v9, v11
	global_store_dwordx4 v[2:3], v[8:11], off offset:224
	s_cbranch_vccnz .LBB0_378
